# grid barriers: every 8th arriving workgroup of an XCC also issues a non-waited L2 write-back, so most dirty lines are already written back when the last arriver does the waited one
# speedup vs baseline: 1.0005x; 1.0005x over previous
; __global__ void __launch_bounds__(NTH, 2) mega_kernel(Params p) {
;     ...
;   grid.sync();
.LBB0_188:
	v_lshrrev_b32_e32 v1, 20, v0
	v_lshrrev_b32_e32 v0, 10, v0
	v_or_b32_e32 v0, v0, v1
	s_movk_i32 s4, 0x3ff
	v_and_or_b32 v0, v0, s4, v220
	v_cmp_eq_u32_e64 s[72:73], 0, v0
	s_waitcnt vmcnt(0) lgkmcnt(0)
	s_barrier
	s_and_saveexec_b64 s[4:5], s[72:73]
	s_cbranch_execz .LBB0_198
	s_load_dwordx2 s[6:7], s[0:1], 0x158
	s_load_dword s8, s[0:1], 0x490
	s_getreg_b32 s9, hwreg(HW_REG_XCC_ID, 0, 4)
	v_mov_b32_e32 v0, 0
	v_mov_b32_e32 v1, 1
	s_lshl_b32 s9, s9, 2
	v_mov_b32_e32 v3, s9
	s_waitcnt lgkmcnt(0)
	global_atomic_add v2, v3, v1, s[6:7] offset:160 sc0
	global_load_dword v3, v3, s[6:7] offset:192 sc1
	s_mul_i32 s8, s8, 1
	s_waitcnt vmcnt(0)
	v_add_u32_e32 v2, 1, v2
	v_mul_u32_u24_e32 v1, 1, v3
	v_cmp_ne_u32_e32 vcc, v1, v2
	s_cbranch_vccnz .Lgs1_wait
	buffer_wbl2 sc1
	s_waitcnt vmcnt(0)
	global_atomic_add v0, v3, s[6:7] offset:136
	s_branch .Lgs1_wait2
.Lgs1_wait:
	v_and_b32_e32 v1, 7, v2
	v_cmp_eq_u32_e32 vcc, 0, v1
	s_cbranch_vccz .Lgs1_wait2
	buffer_wbl2 sc1

; #define RUNPH(k, call) for (int rep_ = 0; rep_ < (((REPMASK) >> (k)) & 1) + 1; ++rep_) { call; grid.sync(); }
; __global__ void __launch_bounds__(NTH, 2) mega_kernel(Params p) {
;     ...
;   RUNPH(2, phase2(p, smem))
.LBB0_302:
	s_waitcnt vmcnt(0) lgkmcnt(0)
	s_barrier
	s_and_saveexec_b64 s[4:5], s[72:73]
	s_cbranch_execz .LBB0_312
	s_load_dwordx2 s[6:7], s[0:1], 0x158
	s_load_dword s8, s[0:1], 0x490
	s_getreg_b32 s9, hwreg(HW_REG_XCC_ID, 0, 4)
	v_mov_b32_e32 v0, 0
	v_mov_b32_e32 v1, 1
	s_lshl_b32 s9, s9, 2
	v_mov_b32_e32 v3, s9
	s_waitcnt lgkmcnt(0)
	global_atomic_add v2, v3, v1, s[6:7] offset:160 sc0
	global_load_dword v3, v3, s[6:7] offset:192 sc1
	s_mul_i32 s8, s8, 2
	s_waitcnt vmcnt(0)
	v_add_u32_e32 v2, 1, v2
	v_mul_u32_u24_e32 v1, 2, v3
	v_cmp_ne_u32_e32 vcc, v1, v2
	s_cbranch_vccnz .Lgs2_wait
	buffer_wbl2 sc1
	s_waitcnt vmcnt(0)
	global_atomic_add v0, v3, s[6:7] offset:136
	s_branch .Lgs2_wait2

; #define RUNPH(k, call) for (int rep_ = 0; rep_ < (((REPMASK) >> (k)) & 1) + 1; ++rep_) { call; grid.sync(); }
; __global__ void __launch_bounds__(NTH, 2) mega_kernel(Params p) {
;     ...
;   RUNPH(3, phase3(p, smem))
.LBB0_525:
	s_waitcnt vmcnt(0) lgkmcnt(0)
	s_barrier
	s_and_saveexec_b64 s[4:5], s[72:73]
	s_cbranch_execz .LBB0_535
	s_load_dwordx2 s[6:7], s[0:1], 0x158
	s_load_dword s8, s[0:1], 0x490
	s_getreg_b32 s9, hwreg(HW_REG_XCC_ID, 0, 4)
	v_mov_b32_e32 v0, 0
	v_mov_b32_e32 v1, 1
	s_lshl_b32 s9, s9, 2
	v_mov_b32_e32 v3, s9
	s_waitcnt lgkmcnt(0)
	global_atomic_add v2, v3, v1, s[6:7] offset:160 sc0
	global_load_dword v3, v3, s[6:7] offset:192 sc1
	s_mul_i32 s8, s8, 3
	s_waitcnt vmcnt(0)
	v_add_u32_e32 v2, 1, v2
	v_mul_u32_u24_e32 v1, 3, v3
	v_cmp_ne_u32_e32 vcc, v1, v2
	s_cbranch_vccnz .Lgs3_wait
	buffer_wbl2 sc1
	s_waitcnt vmcnt(0)
	global_atomic_add v0, v3, s[6:7] offset:136
	s_branch .Lgs3_wait2

; #define RUNPH(k, call) for (int rep_ = 0; rep_ < (((REPMASK) >> (k)) & 1) + 1; ++rep_) { call; grid.sync(); }
; __global__ void __launch_bounds__(NTH, 2) mega_kernel(Params p) {
;     ...
;   RUNPH(4, phase4(p, smem))
.LBB0_645:
	s_waitcnt vmcnt(0) lgkmcnt(0)
	s_barrier
	s_and_saveexec_b64 s[4:5], s[72:73]
	s_cbranch_execz .LBB0_655
	s_load_dwordx2 s[6:7], s[0:1], 0x158
	s_load_dword s8, s[0:1], 0x490
	s_getreg_b32 s9, hwreg(HW_REG_XCC_ID, 0, 4)
	v_mov_b32_e32 v0, 0
	v_mov_b32_e32 v1, 1
	s_lshl_b32 s9, s9, 2
	v_mov_b32_e32 v3, s9
	s_waitcnt lgkmcnt(0)
	global_atomic_add v2, v3, v1, s[6:7] offset:160 sc0
	global_load_dword v3, v3, s[6:7] offset:192 sc1
	s_mul_i32 s8, s8, 4
	s_waitcnt vmcnt(0)
	v_add_u32_e32 v2, 1, v2
	v_mul_u32_u24_e32 v1, 4, v3
	v_cmp_ne_u32_e32 vcc, v1, v2
	s_cbranch_vccnz .Lgs4_wait
	buffer_wbl2 sc1
	s_waitcnt vmcnt(0)
	global_atomic_add v0, v3, s[6:7] offset:136
	s_branch .Lgs4_wait2

; #define RUNPH(k, call) for (int rep_ = 0; rep_ < (((REPMASK) >> (k)) & 1) + 1; ++rep_) { call; grid.sync(); }
; __global__ void __launch_bounds__(NTH, 2) mega_kernel(Params p) {
;     ...
;   RUNPH(5, phase5(p, smem))
.LBB0_882:
	s_waitcnt vmcnt(0) lgkmcnt(0)
	s_barrier
	s_and_saveexec_b64 s[4:5], s[72:73]
	s_cbranch_execz .LBB0_892
	s_load_dwordx2 s[6:7], s[0:1], 0x158
	s_load_dword s8, s[0:1], 0x490
	s_getreg_b32 s9, hwreg(HW_REG_XCC_ID, 0, 4)
	v_mov_b32_e32 v0, 0
	v_mov_b32_e32 v1, 1
	s_lshl_b32 s9, s9, 2
	v_mov_b32_e32 v3, s9
	s_waitcnt lgkmcnt(0)
	global_atomic_add v2, v3, v1, s[6:7] offset:160 sc0
	global_load_dword v3, v3, s[6:7] offset:192 sc1
	s_mul_i32 s8, s8, 5
	s_waitcnt vmcnt(0)
	v_add_u32_e32 v2, 1, v2
	v_mul_u32_u24_e32 v1, 5, v3
	v_cmp_ne_u32_e32 vcc, v1, v2
	s_cbranch_vccnz .Lgs5_wait
	buffer_wbl2 sc1
	s_waitcnt vmcnt(0)
	global_atomic_add v0, v3, s[6:7] offset:136
	s_branch .Lgs5_wait2

; #define RUNPH(k, call) for (int rep_ = 0; rep_ < (((REPMASK) >> (k)) & 1) + 1; ++rep_) { call; grid.sync(); }
; __global__ void __launch_bounds__(NTH, 2) mega_kernel(Params p) {
;     ...
;   RUNPH(6, phase6(p, smem))
.LBB0_929:
	s_waitcnt vmcnt(0) lgkmcnt(0)
	s_barrier
	s_and_saveexec_b64 s[4:5], s[72:73]
	s_cbranch_execz .LBB0_939
	s_load_dwordx2 s[6:7], s[0:1], 0x158
	s_load_dword s8, s[0:1], 0x490
	s_getreg_b32 s9, hwreg(HW_REG_XCC_ID, 0, 4)
	v_mov_b32_e32 v0, 0
	v_mov_b32_e32 v1, 1
	s_lshl_b32 s9, s9, 2
	v_mov_b32_e32 v3, s9
	s_waitcnt lgkmcnt(0)
	global_atomic_add v2, v3, v1, s[6:7] offset:160 sc0
	global_load_dword v3, v3, s[6:7] offset:192 sc1
	s_mul_i32 s8, s8, 6
	s_waitcnt vmcnt(0)
	v_add_u32_e32 v2, 1, v2
	v_mul_u32_u24_e32 v1, 6, v3
	v_cmp_ne_u32_e32 vcc, v1, v2
	s_cbranch_vccnz .Lgs6_wait
	buffer_wbl2 sc1
	s_waitcnt vmcnt(0)
	global_atomic_add v0, v3, s[6:7] offset:136
	s_branch .Lgs6_wait2

; #define RUNPH(k, call) for (int rep_ = 0; rep_ < (((REPMASK) >> (k)) & 1) + 1; ++rep_) { call; grid.sync(); }
; __global__ void __launch_bounds__(NTH, 2) mega_kernel(Params p) {
;     ...
;   RUNPH(7, phase7(p, smem))
.LBB0_968:
	s_or_b64 exec, exec, s[18:19]
	s_waitcnt vmcnt(0) lgkmcnt(0)
	s_barrier
	s_and_saveexec_b64 s[4:5], s[72:73]
	s_cbranch_execz .LBB0_978
	s_load_dwordx2 s[6:7], s[0:1], 0x158
	s_load_dword s8, s[0:1], 0x490
	s_getreg_b32 s9, hwreg(HW_REG_XCC_ID, 0, 4)
	v_mov_b32_e32 v0, 0
	v_mov_b32_e32 v1, 1
	s_lshl_b32 s9, s9, 2
	v_mov_b32_e32 v3, s9
	s_waitcnt lgkmcnt(0)
	global_atomic_add v2, v3, v1, s[6:7] offset:160 sc0
	global_load_dword v3, v3, s[6:7] offset:192 sc1
	s_mul_i32 s8, s8, 7
	s_waitcnt vmcnt(0)
	v_add_u32_e32 v2, 1, v2
	v_mul_u32_u24_e32 v1, 7, v3
	v_cmp_ne_u32_e32 vcc, v1, v2
	s_cbranch_vccnz .Lgs7_wait
	buffer_wbl2 sc1
	s_waitcnt vmcnt(0)
	global_atomic_add v0, v3, s[6:7] offset:136
	s_branch .Lgs7_wait2

; #define RUNPH(k, call) for (int rep_ = 0; rep_ < (((REPMASK) >> (k)) & 1) + 1; ++rep_) { call; grid.sync(); }
; __global__ void __launch_bounds__(NTH, 2) mega_kernel(Params p) {
;     ...
;   RUNPH(8, phase8(p))
.LBB0_1175:
	s_or_b64 exec, exec, s[88:89]
	s_waitcnt vmcnt(0) lgkmcnt(0)
	s_barrier
	s_and_saveexec_b64 s[4:5], s[72:73]
	s_cbranch_execz .LBB0_1185
	s_load_dwordx2 s[6:7], s[0:1], 0x158
	s_load_dword s8, s[0:1], 0x490
	s_getreg_b32 s9, hwreg(HW_REG_XCC_ID, 0, 4)
	v_mov_b32_e32 v0, 0
	v_mov_b32_e32 v1, 1
	s_lshl_b32 s9, s9, 2
	v_mov_b32_e32 v3, s9
	s_waitcnt lgkmcnt(0)
	global_atomic_add v2, v3, v1, s[6:7] offset:160 sc0
	global_load_dword v3, v3, s[6:7] offset:192 sc1
	s_mul_i32 s8, s8, 8
	s_waitcnt vmcnt(0)
	v_add_u32_e32 v2, 1, v2
	v_mul_u32_u24_e32 v1, 8, v3
	v_cmp_ne_u32_e32 vcc, v1, v2
	s_cbranch_vccnz .Lgs8_wait
	buffer_wbl2 sc1
	s_waitcnt vmcnt(0)
	global_atomic_add v0, v3, s[6:7] offset:136
	s_branch .Lgs8_wait2

; __global__ void __launch_bounds__(NTH, 2) mega_kernel(Params p) {
;     ...
;   grid.sync();
.LBB0_1372:
	s_waitcnt vmcnt(0) lgkmcnt(0)
	s_barrier
	s_and_saveexec_b64 s[2:3], s[72:73]
	s_cbranch_execz .LBB0_1382
	s_load_dwordx2 s[6:7], s[0:1], 0x158
	s_load_dword s8, s[0:1], 0x490
	s_getreg_b32 s9, hwreg(HW_REG_XCC_ID, 0, 4)
	v_mov_b32_e32 v0, 0
	v_mov_b32_e32 v1, 1
	s_lshl_b32 s9, s9, 2
	v_mov_b32_e32 v3, s9
	s_waitcnt lgkmcnt(0)
	global_atomic_add v2, v3, v1, s[6:7] offset:160 sc0
	global_load_dword v3, v3, s[6:7] offset:192 sc1
	s_mul_i32 s8, s8, 9
	s_waitcnt vmcnt(0)
	v_add_u32_e32 v2, 1, v2
	v_mul_u32_u24_e32 v1, 9, v3
	v_cmp_ne_u32_e32 vcc, v1, v2
	s_cbranch_vccnz .Lgs9_wait
	buffer_wbl2 sc1
	s_waitcnt vmcnt(0)
	global_atomic_add v0, v3, s[6:7] offset:136
	s_branch .Lgs9_wait2
